# sample attention: per-unit lane constants (image fragment addresses) hoisted out of the tile loop; f32-stage reads of the conversion pass issued in one burst
# speedup vs baseline: 1.0101x; 1.0013x over previous
.LBB0_800:
	s_or_b64 exec, exec, s[0:1]
	v_and_b32_e32 v215, 15, v250
	v_lshl_or_b32 v2, s19, 7, v215
	v_ashrrev_i32_e32 v3, 31, v2
	v_readlane_b32 s40, v253, 24
	v_lshlrev_b64 v[2:3], 9, v[2:3]
	v_readlane_b32 s48, v253, 32
	v_readlane_b32 s49, v253, 33
	s_movk_i32 s0, 0x2000
	s_and_b32 s8, s14, 0x80000001
	v_lshl_add_u64 v[4:5], s[48:49], 0, v[2:3]
	v_and_b32_e32 v2, 48, v214
	v_mov_b32_e32 v3, v191
	v_lshl_add_u64 v[4:5], v[4:5], 0, v[2:3]
	v_add_co_u32_e32 v10, vcc, s0, v4
	s_movk_i32 s0, 0x4000
	s_nop 0
	v_addc_co_u32_e32 v11, vcc, 0, v5, vcc
	global_load_dwordx4 v[50:53], v[4:5], off
	global_load_dwordx4 v[54:57], v[4:5], off offset:64
	global_load_dwordx4 v[58:61], v[4:5], off offset:128
	global_load_dwordx4 v[62:65], v[4:5], off offset:192
	global_load_dwordx4 v[66:69], v[4:5], off offset:256
	global_load_dwordx4 v[70:73], v[4:5], off offset:320
	global_load_dwordx4 v[74:77], v[4:5], off offset:384
	global_load_dwordx4 v[78:81], v[4:5], off offset:448
	global_load_dwordx4 v[82:85], v[10:11], off
	global_load_dwordx4 v[86:89], v[10:11], off offset:64
	global_load_dwordx4 v[90:93], v[10:11], off offset:128
	global_load_dwordx4 v[94:97], v[10:11], off offset:192
	global_load_dwordx4 v[98:101], v[10:11], off offset:256
	global_load_dwordx4 v[102:105], v[10:11], off offset:320
	global_load_dwordx4 v[106:109], v[10:11], off offset:384
	global_load_dwordx4 v[110:113], v[10:11], off offset:448
	v_add_co_u32_e32 v10, vcc, s0, v4
	s_movk_i32 s0, 0x6000
	s_nop 0
	v_addc_co_u32_e32 v11, vcc, 0, v5, vcc
	v_add_co_u32_e32 v4, vcc, s0, v4
	global_load_dwordx4 v[114:117], v[10:11], off
	global_load_dwordx4 v[118:121], v[10:11], off offset:64
	global_load_dwordx4 v[122:125], v[10:11], off offset:128
	global_load_dwordx4 v[126:129], v[10:11], off offset:192
	global_load_dwordx4 v[130:133], v[10:11], off offset:256
	global_load_dwordx4 v[134:137], v[10:11], off offset:320
	global_load_dwordx4 v[138:141], v[10:11], off offset:384
	global_load_dwordx4 v[142:145], v[10:11], off offset:448
	v_addc_co_u32_e32 v5, vcc, 0, v5, vcc
	global_load_dwordx4 v[146:149], v[4:5], off
	global_load_dwordx4 v[150:153], v[4:5], off offset:64
	global_load_dwordx4 v[154:157], v[4:5], off offset:128
	global_load_dwordx4 v[158:161], v[4:5], off offset:192
	global_load_dwordx4 v[162:165], v[4:5], off offset:256
	global_load_dwordx4 v[166:169], v[4:5], off offset:320
	global_load_dwordx4 v[170:173], v[4:5], off offset:384
	global_load_dwordx4 v[174:177], v[4:5], off offset:448
	v_add_u32_e32 v4, s15, v215
	s_movk_i32 s0, 0x68
	v_mul_lo_u32 v4, v4, s0
	v_cmp_gt_u32_e64 s[0:1], 8, v215
	s_cmp_eq_u32 s8, 1
	s_cselect_b32 s37, 0x41, 64
	v_cndmask_b32_e64 v34, v210, v4, s[0:1]
	v_mov_b32_e32 v4, v0
	s_add_i32 s38, 0, 0x1f400
	s_lshl_b32 s11, s18, 6
	s_and_b32 s11, s11, 0xffffc000
	s_add_i32 s39, s11, 0
	s_lshl_b32 s11, s19, 2
	v_readlane_b32 s44, v253, 28
	v_readlane_b32 s45, v253, 29
	v_readlane_b32 s46, v253, 30
	v_readlane_b32 s47, v253, 31
	v_readlane_b32 s50, v253, 34
	v_readlane_b32 s51, v253, 35
	v_readlane_b32 s52, v253, 36
	v_readlane_b32 s53, v253, 37
	v_readlane_b32 s54, v253, 38
	v_readlane_b32 s55, v253, 39
	v_lshrrev_b32_e32 v3, 4, v214
	s_and_b32 s40, s11, 12
	v_lshl_add_u32 v221, v7, 2, 0
	s_movk_i32 s11, 0x8c
	v_lshlrev_b32_e32 v216, 3, v3
	v_lshlrev_b32_e32 v218, 2, v3
	v_mad_u32_u24 v3, v7, s11, v221
	s_movk_i32 s11, 0x800
	v_readlane_b32 s44, v254, 28
	v_readlane_b32 s42, v253, 26
	v_readlane_b32 s43, v253, 27
	v_cmp_gt_i32_e64 s[12:13], s11, v250
	s_movk_i32 s11, 0xff72
	v_readlane_b32 s46, v254, 30
	v_readlane_b32 s47, v254, 31
	v_mad_i32_i24 v194, v7, s11, v3
	v_lshl_add_u64 v[196:197], s[84:85], 0, v[190:191]
	v_lshlrev_b32_e32 v190, 4, v7
	v_readlane_b32 s45, v254, 29
	v_readlane_b32 s48, v254, 32
	v_readlane_b32 s49, v254, 33
	v_readlane_b32 s50, v254, 34
	v_readlane_b32 s51, v254, 35
	v_readlane_b32 s52, v254, 36
	v_readlane_b32 s53, v254, 37
	s_waitcnt vmcnt(0)
	s_waitcnt vmcnt(0)
	v_readlane_b32 s54, v254, 38
	v_lshrrev_b32_e32 v5, 3, v4
	v_bfe_u32 v8, v4, 5, 1
	v_and_or_b32 v5, v5, s28, v8
	v_lshlrev_b32_e32 v8, 5, v4
	v_and_b32_e32 v8, 0x3e0, v8
	v_lshlrev_b32_e32 v5, 10, v5
	v_add3_u32 v5, 0, v8, v5
	ds_read_b128 v[10:13], v5 offset:62464
	ds_read_b128 v[14:17], v5 offset:62480
	v_add_u32_e32 v8, 0xf400, v5
	ds_read_b128 v[18:21], v5 offset:64512
	ds_read_b128 v[22:25], v8 offset:4096
	ds_read_b128 v[26:29], v8 offset:4112
	s_waitcnt lgkmcnt(0)
	v_cvt_pk_bf16_f32 v10, v10, v11
	v_cvt_pk_bf16_f32 v11, v12, v13
	v_cvt_pk_bf16_f32 v12, v14, v15
	v_cvt_pk_bf16_f32 v13, v16, v17
	ds_read_b128 v[14:17], v5 offset:64528
	v_lshlrev_b32_e32 v4, 4, v4
	v_and_b32_e32 v5, 0xffffff80, v4
	v_and_b32_e32 v4, 0x70, v4
	v_cvt_pk_bf16_f32 v18, v18, v19
	v_cvt_pk_bf16_f32 v19, v20, v21
	s_waitcnt lgkmcnt(0)
	v_cvt_pk_bf16_f32 v20, v14, v15
	v_cvt_pk_bf16_f32 v21, v16, v17
	v_cvt_pk_bf16_f32 v14, v22, v23
	v_cvt_pk_bf16_f32 v15, v24, v25
	v_cvt_pk_bf16_f32 v16, v26, v27
	v_cvt_pk_bf16_f32 v17, v28, v29
	ds_read_b128 v[22:25], v8 offset:6144
	ds_read_b128 v[26:29], v8 offset:6160
	v_add3_u32 v4, s38, v5, v4
	ds_read_b128 v[30:33], v4
	v_mov_b32_e32 v8, v0
	s_waitcnt lgkmcnt(2)
	v_cvt_pk_bf16_f32 v22, v22, v23
	v_cvt_pk_bf16_f32 v23, v24, v25
	s_waitcnt lgkmcnt(1)
	v_cvt_pk_bf16_f32 v24, v26, v27
	v_cvt_pk_bf16_f32 v25, v28, v29
	v_ashrrev_i32_e32 v26, 3, v8
	s_waitcnt lgkmcnt(0)
	v_cvt_pk_bf16_f32 v5, v32, v33
	v_bfe_u32 v28, v8, 5, 1
	v_lshrrev_b32_e32 v33, 2, v26
	v_cvt_pk_bf16_f32 v4, v30, v31
	v_and_b32_e32 v27, -8, v26
	v_lshlrev_b32_e32 v29, 10, v8
	v_and_b32_e32 v30, 15, v8
	v_and_b32_e32 v33, 2, v33
	v_lshlrev_b32_e32 v35, 2, v28
	v_and_b32_e32 v29, 0x4000, v29
	v_or_b32_e32 v31, v27, v28
	v_bitop3_b32 v36, v35, v30, v33 bitop3:0x36
	v_add_u32_e32 v29, 0, v29
	v_lshlrev_b32_e32 v32, 8, v31
	v_lshlrev_b32_e32 v36, 4, v36
	v_add3_u32 v32, v29, v36, v32
	ds_write_b128 v32, v[10:13]
	v_or_b32_e32 v10, 2, v31
	v_lshlrev_b32_e32 v11, 8, v10
	v_lshlrev_b32_e32 v10, 2, v10
	v_and_b32_e32 v10, 12, v10
	v_bitop3_b32 v10, v10, v30, v33 bitop3:0x36
	v_lshlrev_b32_e32 v10, 4, v10
	v_add3_u32 v10, v29, v10, v11
	ds_write_b128 v10, v[18:21]
	v_or_b32_e32 v10, 4, v27
	v_or_b32_e32 v11, v10, v28
	v_bfe_u32 v10, v10, 2, 2
	v_bitop3_b32 v10, v35, v30, v10 bitop3:0x36
	v_lshlrev_b32_e32 v11, 8, v11
	v_lshlrev_b32_e32 v10, 4, v10
	v_add3_u32 v10, v29, v10, v11
	ds_write_b128 v10, v[14:17]
	v_or_b32_e32 v10, 6, v27
	v_or_b32_e32 v11, v10, v28
	v_lshlrev_b32_e32 v12, 8, v11
	v_lshlrev_b32_e32 v11, 2, v11
	v_and_b32_e32 v11, 12, v11
	v_bfe_u32 v10, v10, 2, 2
	v_bitop3_b32 v10, v11, v30, v10 bitop3:0x36
	v_lshlrev_b32_e32 v10, 4, v10
	v_lshlrev_b32_e32 v8, 2, v8
	v_add3_u32 v10, v29, v10, v12
	v_and_b32_e32 v8, 28, v8
	ds_write_b128 v10, v[22:25]
	v_mad_u64_u32 v[10:11], s[8:9], v26, 40, v[8:9]
	v_lshl_add_u32 v8, v10, 1, 0
	ds_write_b64 v8, v[4:5] offset:32768
	v_lshlrev_b32_e32 v4, 1, v34
	v_add3_u32 v219, 0, v4, v216
	v_lshrrev_b32_e32 v4, 1, v250
	v_readlane_b32 s55, v254, 39
	s_mov_b64 s[42:43], s[46:47]
	s_lshl_b32 s11, s19, 5
	v_and_b32_e32 v4, 16, v4
	v_readlane_b32 s56, v254, 40
	v_readlane_b32 s57, v254, 41
	v_readlane_b32 s58, v254, 42
	v_readlane_b32 s59, v254, 43
	s_mov_b64 s[44:45], s[48:49]
	v_lshl_add_u64 v[198:199], s[42:43], 0, v[190:191]
	v_lshlrev_b32_e32 v190, 1, v7
	s_add_i32 s11, s11, 0xecd0
	s_waitcnt lgkmcnt(0)
	s_barrier
	v_add_u32_e32 v222, v3, v4
	v_lshlrev_b32_e32 v4, 10, v7
	v_lshl_add_u64 v[200:201], s[44:45], 0, v[190:191]
	v_lshl_add_u32 v190, v215, 2, s11
	s_mul_i32 s11, s19, 0x480
	v_and_b32_e32 v4, 0x4000, v4
	v_mov_b32_e32 v7, v191
	s_add_i32 s11, s11, 0x9400
	v_mul_u32_u24_e32 v3, 0x90, v215
	v_mad_u32_u24 v2, v215, s29, v2
	v_mov_b32_e32 v217, 0
	s_mov_b32 s10, 0
	v_mov_b32_e32 v193, s17
	v_or_b32_e32 v192, s15, v9
	v_min_u32_e32 v220, 7, v215
	v_cmp_gt_u32_e64 s[8:9], 16, v214
	v_add_u32_e32 v223, 0, v4
	v_lshl_add_u64 v[212:213], s[82:83], 0, v[6:7]
	v_add3_u32 v224, s11, v3, v216
	v_or_b32_e32 v225, 0x8000, v2
	v_mov_b32_e32 v42, 0xff800000
	v_mov_b32_e32 v2, 0
	v_mov_b32_e32 v3, v217
	v_mov_b32_e32 v4, v217
	v_mov_b32_e32 v5, v217
	v_mov_b32_e32 v6, v217
	v_mov_b32_e32 v7, v217
	v_mov_b32_e32 v8, v217
	v_mov_b32_e32 v9, v217
	v_mov_b32_e32 v10, v217
	v_mov_b32_e32 v11, v217
	v_mov_b32_e32 v12, v217
	v_mov_b32_e32 v13, v217
	v_mov_b32_e32 v14, v217
	v_mov_b32_e32 v15, v217
	v_mov_b32_e32 v16, v217
	v_mov_b32_e32 v17, v217
	v_mov_b32_e32 v18, 0
	v_mov_b32_e32 v19, v217
	v_mov_b32_e32 v20, v217
	v_mov_b32_e32 v21, v217
	v_mov_b32_e32 v22, v217
	v_mov_b32_e32 v23, v217
	v_mov_b32_e32 v24, v217
	v_mov_b32_e32 v25, v217
	v_mov_b32_e32 v26, v217
	v_mov_b32_e32 v27, v217
	v_mov_b32_e32 v28, v217
	v_mov_b32_e32 v29, v217
	v_mov_b32_e32 v30, v217
	v_mov_b32_e32 v31, v217
	v_mov_b32_e32 v32, v217
	v_mov_b32_e32 v33, v217
	v_readlane_b32 s41, v253, 25
	s_mov_b64 s[46:47], s[50:51]
	s_mov_b64 s[48:49], s[52:53]
	s_mov_b64 s[50:51], s[54:55]
	s_mov_b64 s[52:53], s[56:57]
	s_mov_b64 s[54:55], s[58:59]
	v_lshrrev_b32_e32 v45, 4, v214
	v_lshlrev_b32_e32 v34, 2, v214
	v_and_b32_e32 v34, 12, v34
	v_bfe_u32 v35, v214, 2, 2
	v_add_u32_e32 v38, 8, v45
	v_add_u32_e32 v37, 4, v45
	v_bitop3_b32 v47, v34, v38, v35 bitop3:0x36
	v_add_u32_e32 v38, 12, v45
	v_bitop3_b32 v36, v34, v45, v35 bitop3:0x36
	v_bitop3_b32 v37, v34, v37, v35 bitop3:0x36
	v_bitop3_b32 v46, v34, v38, v35 bitop3:0x36
	v_lshlrev_b32_e32 v34, 8, v214
	v_and_b32_e32 v34, 0xf00, v34
	v_lshrrev_b32_e32 v44, 2, v214
	v_lshl_add_u32 v46, v46, 4, v34
	v_lshl_add_u32 v47, v47, 4, v34
	v_lshl_add_u32 v48, v37, 4, v34
	v_lshl_add_u32 v49, v36, 4, v34
	v_lshrrev_b32_e32 v34, 3, v214
	v_and_b32_e32 v38, 12, v214
	v_and_or_b32 v34, v34, 2, s40
	v_bfe_u32 v35, v214, 1, 1
	v_and_or_b32 v39, v45, 2, v38
	v_or_b32_e32 v36, v34, v35
	v_lshlrev_b32_e32 v37, 8, v44
	v_bitop3_b32 v34, v34, v39, v35 bitop3:0x36
	v_lshlrev_b32_e32 v35, 3, v214
	v_and_b32_e32 v37, 0xfffffb00, v37
	v_and_b32_e32 v35, 8, v35
	v_lshl_add_u32 v34, v34, 4, s39
	v_add3_u32 v34, v34, v37, v35
	v_or_b32_e32 v37, 4, v44
	v_lshlrev_b32_e32 v39, 8, v37
	v_bfe_u32 v37, v37, 2, 2
	v_bitop3_b32 v36, v37, v36, v38 bitop3:0x36
	v_lshl_add_u32 v36, v36, 4, s39
	v_add3_u32 v35, v36, v39, v35
	v_mov_b32_e32 v43, v34
	v_mov_b32_e32 v44, v35
.LBB0_801:
	s_add_i32 s41, s10, 1
	s_cmp_lt_u32 s10, 63
	s_cselect_b64 s[20:21], -1, 0
	s_cmp_gt_u32 s10, 62
	s_cselect_b64 s[18:19], -1, 0
	s_mov_b64 s[24:25], 0
	s_and_b64 vcc, exec, s[18:19]
	s_cbranch_vccnz .LBB0_803
	s_lshr_b32 s22, s41, 1
	v_readlane_b32 s22, v252, s22
	s_lshl_b32 s11, s41, 6
	s_ashr_i32 s23, s22, 31
	s_and_b32 s11, s11, 64
	s_lshl_b64 s[24:25], s[22:23], 7
	s_or_b32 s24, s24, s11
.LBB0_803:
	s_cmp_eq_u32 s10, 64
	v_lshl_add_u64 v[34:35], v[192:193], 0, s[24:25]
	s_cselect_b64 s[22:23], -1, 0
	v_lshlrev_b64 v[34:35], 7, v[34:35]
	s_add_u32 s10, s15, s24
	v_lshl_add_u64 v[38:39], v[196:197], 0, v[34:35]
	s_addc_u32 s11, s17, s25
	s_lshl_b64 s[10:11], s[10:11], 10
	v_lshl_add_u64 v[40:41], v[212:213], 0, s[10:11]
	s_and_b64 vcc, exec, s[20:21]
	s_mov_b64 s[24:25], 0x1000
	v_add_u32_e32 v207, 0xb800, v219
	v_add_u32_e32 v208, v219, v216
	ds_read_b128 v[34:37], v49
	ds_read_b128 v[182:185], v48
	ds_read_b128 v[186:189], v47
	ds_read_b128 v[202:205], v46
	s_waitcnt lgkmcnt(2)
	v_mfma_f32_16x16x32_bf16 v[226:229], v[50:53], v[34:37], 0
	v_mfma_f32_16x16x32_bf16 v[230:233], v[82:85], v[34:37], 0
	v_mfma_f32_16x16x32_bf16 v[234:237], v[114:117], v[34:37], 0
	v_mfma_f32_16x16x32_bf16 v[238:241], v[146:149], v[34:37], 0
	s_cbranch_vccz .Lsa_nd0
	s_add_i32 m0, s35, 0xf400
	s_nop 0
	global_load_lds_dwordx4 v[40:41], off nt

.Lsa_pdone:
	s_or_b64 exec, exec, s[24:25]
	v_add_u32_e32 v40, 0xec00, v221
	s_waitcnt lgkmcnt(0)
	s_barrier
	ds_read2_b32 v[202:203], v40 offset0:52 offset1:84
	ds_read_b64_tr_b16 v[226:227], v43
	ds_read_b64_tr_b16 v[228:229], v44
	ds_read_b64_tr_b16 v[186:187], v43 offset:4096
	ds_read_b64_tr_b16 v[188:189], v44 offset:4096
	ds_read_b64_tr_b16 v[182:183], v43 offset:8192
	ds_read_b64_tr_b16 v[184:185], v44 offset:8192
	ds_read_b64_tr_b16 v[178:179], v43 offset:12288
	ds_read_b64_tr_b16 v[180:181], v44 offset:12288
	s_waitcnt lgkmcnt(8)
	v_pk_mul_f32 v[2:3], v[202:203], v[2:3] op_sel_hi:[0,1]
	v_pk_mul_f32 v[4:5], v[202:203], v[4:5] op_sel_hi:[0,1]
	v_pk_mul_f32 v[6:7], v[202:203], v[6:7] op_sel_hi:[0,1]
	v_pk_mul_f32 v[8:9], v[202:203], v[8:9] op_sel_hi:[0,1]
	v_pk_mul_f32 v[10:11], v[202:203], v[10:11] op_sel_hi:[0,1]
	v_pk_mul_f32 v[12:13], v[202:203], v[12:13] op_sel_hi:[0,1]
	v_pk_mul_f32 v[14:15], v[202:203], v[14:15] op_sel_hi:[0,1]
	v_pk_mul_f32 v[16:17], v[202:203], v[16:17] op_sel_hi:[0,1]
	v_pk_mul_f32 v[18:19], v[202:203], v[18:19] op_sel:[1,0]
	v_pk_mul_f32 v[20:21], v[202:203], v[20:21] op_sel:[1,0]
	v_pk_mul_f32 v[22:23], v[202:203], v[22:23] op_sel:[1,0]
	v_pk_mul_f32 v[24:25], v[202:203], v[24:25] op_sel:[1,0]
	v_pk_mul_f32 v[26:27], v[202:203], v[26:27] op_sel:[1,0]
	v_pk_mul_f32 v[28:29], v[202:203], v[28:29] op_sel:[1,0]
	v_pk_mul_f32 v[30:31], v[202:203], v[30:31] op_sel:[1,0]
	v_pk_mul_f32 v[32:33], v[202:203], v[32:33] op_sel:[1,0]
	s_waitcnt lgkmcnt(4)
	ds_read_b128 v[230:233], v222 offset:37888
	ds_read_b128 v[234:237], v222 offset:42496
	ds_read_b128 v[238:241], v222 offset:37920
	ds_read_b128 v[242:245], v222 offset:42528
	ds_read_b128 v[246:249], v222 offset:37952
	ds_read_b128 v[206:209], v222 offset:42560
	ds_read_b128 v[34:37], v222 offset:37984
	ds_read_b128 v[38:41], v222 offset:42592
	s_waitcnt lgkmcnt(6)
	v_mfma_f32_32x32x16_bf16 v[2:17], v[226:229], v[230:233], v[2:17]
	v_mfma_f32_32x32x16_bf16 v[18:33], v[226:229], v[234:237], v[18:33]
	s_waitcnt lgkmcnt(4)
	v_mfma_f32_32x32x16_bf16 v[2:17], v[186:189], v[238:241], v[2:17]
	v_mfma_f32_32x32x16_bf16 v[18:33], v[186:189], v[242:245], v[18:33]
	s_waitcnt lgkmcnt(2)
	v_mfma_f32_32x32x16_bf16 v[2:17], v[182:185], v[246:249], v[2:17]
	v_mfma_f32_32x32x16_bf16 v[18:33], v[182:185], v[206:209], v[18:33]
	s_waitcnt lgkmcnt(0)
	v_mfma_f32_32x32x16_bf16 v[2:17], v[178:181], v[34:37], v[2:17]
	v_mfma_f32_32x32x16_bf16 v[18:33], v[178:181], v[38:41], v[18:33]
	s_cmp_lt_u32 s41, s37
	s_cbranch_scc0 .LBB0_828
	s_mov_b64 s[10:11], -1
	s_and_b64 vcc, exec, s[18:19]
	s_cbranch_vccz .LBB0_825
	s_waitcnt lgkmcnt(0)
	s_barrier
	s_and_saveexec_b64 s[18:19], s[12:13]
	s_cbranch_execz .LBB0_824
	s_mov_b64 s[20:21], 0
	v_mov_b32_e32 v40, v250
	s_branch .LBB0_818

.LBB0_825:
	s_andn2_b64 vcc, exec, s[10:11]
	s_cbranch_vccnz .LBB0_827
	v_mov_b32_e32 v182, v0
	s_waitcnt vmcnt(0)
	v_lshrrev_b32_e32 v34, 3, v182
	v_bfe_u32 v35, v182, 5, 1
	v_and_or_b32 v34, v34, s28, v35
	v_lshlrev_b32_e32 v35, 5, v182
	v_and_b32_e32 v35, 0x3e0, v35
	v_lshlrev_b32_e32 v34, 10, v34
	v_add3_u32 v42, 0, v35, v34
	v_add_u32_e32 v183, 0xf400, v42
	v_lshlrev_b32_e32 v184, 4, v182
	v_and_b32_e32 v185, 0xffffff80, v184
	v_and_b32_e32 v184, 0x70, v184
	v_add3_u32 v184, s38, v185, v184
	ds_read_b128 v[34:37], v42 offset:62464
	ds_read_b128 v[38:41], v42 offset:62480
	ds_read_b128 v[226:229], v42 offset:64512
	ds_read_b128 v[230:233], v42 offset:64528
	ds_read_b128 v[234:237], v183 offset:4096
	ds_read_b128 v[238:241], v183 offset:4112
	ds_read_b128 v[242:245], v183 offset:6144
	ds_read_b128 v[246:249], v183 offset:6160
	ds_read_b128 v[178:181], v184
	s_waitcnt lgkmcnt(0)
	v_cvt_pk_bf16_f32 v34, v34, v35
	v_cvt_pk_bf16_f32 v35, v36, v37
	v_cvt_pk_bf16_f32 v36, v38, v39
	v_cvt_pk_bf16_f32 v37, v40, v41
	v_cvt_pk_bf16_f32 v226, v226, v227
	v_cvt_pk_bf16_f32 v227, v228, v229
	v_cvt_pk_bf16_f32 v228, v230, v231
	v_cvt_pk_bf16_f32 v229, v232, v233
	v_cvt_pk_bf16_f32 v234, v234, v235
	v_cvt_pk_bf16_f32 v235, v236, v237
	v_cvt_pk_bf16_f32 v236, v238, v239
	v_cvt_pk_bf16_f32 v237, v240, v241
	v_cvt_pk_bf16_f32 v242, v242, v243
	v_cvt_pk_bf16_f32 v243, v244, v245
	v_cvt_pk_bf16_f32 v244, v246, v247
	v_cvt_pk_bf16_f32 v245, v248, v249
	s_barrier
	s_waitcnt lgkmcnt(0)
	v_cvt_pk_bf16_f32 v178, v178, v179
	v_cvt_pk_bf16_f32 v179, v180, v181
	v_mov_b32_e32 v180, v0
	s_nop 0
	v_ashrrev_i32_e32 v181, 3, v180
	v_bfe_u32 v183, v180, 5, 1
	v_lshrrev_b32_e32 v188, 2, v181
	v_and_b32_e32 v182, -8, v181
	v_lshlrev_b32_e32 v184, 10, v180
	v_and_b32_e32 v185, 15, v180
	v_and_b32_e32 v188, 2, v188
	v_lshlrev_b32_e32 v189, 2, v183
	v_and_b32_e32 v184, 0x4000, v184
	v_or_b32_e32 v186, v182, v183
	v_bitop3_b32 v202, v189, v185, v188 bitop3:0x36
	v_add_u32_e32 v184, 0, v184
	v_lshlrev_b32_e32 v187, 8, v186
	v_lshlrev_b32_e32 v202, 4, v202
	v_add3_u32 v187, v184, v202, v187
	ds_write_b128 v187, v[34:37]
	v_or_b32_e32 v34, 2, v186
	v_lshlrev_b32_e32 v35, 8, v34
	v_lshlrev_b32_e32 v34, 2, v34
	v_and_b32_e32 v34, 12, v34
	v_bitop3_b32 v34, v34, v185, v188 bitop3:0x36
	v_lshlrev_b32_e32 v34, 4, v34
	v_add3_u32 v34, v184, v34, v35
	ds_write_b128 v34, v[226:229]
	v_or_b32_e32 v34, 4, v182
	v_or_b32_e32 v35, v34, v183
	v_bfe_u32 v34, v34, 2, 2
	v_bitop3_b32 v34, v189, v185, v34 bitop3:0x36
	v_lshlrev_b32_e32 v35, 8, v35
	v_lshlrev_b32_e32 v34, 4, v34
	v_add3_u32 v34, v184, v34, v35
	ds_write_b128 v34, v[234:237]
	v_or_b32_e32 v34, 6, v182
	v_or_b32_e32 v35, v34, v183
	v_lshlrev_b32_e32 v36, 8, v35
	v_lshlrev_b32_e32 v35, 2, v35
	v_and_b32_e32 v35, 12, v35
	v_bfe_u32 v34, v34, 2, 2
	v_bitop3_b32 v34, v35, v185, v34 bitop3:0x36
	v_lshlrev_b32_e32 v34, 4, v34
	v_add3_u32 v34, v184, v34, v36
	ds_write_b128 v34, v[242:245]
	v_lshlrev_b32_e32 v34, 2, v180
	v_and_b32_e32 v34, 28, v34
	v_mad_u64_u32 v[34:35], s[10:11], v181, 40, v[34:35]
	v_lshl_add_u32 v34, v34, 1, 0
	ds_write_b64 v34, v[178:179] offset:32768
